# P1: six of eight epilogue row-blocks deferred into the next unit's first K-iteration
# speedup vs baseline: 1.0022x; 1.0022x over previous
; #define PG8_STAGE(bufoff, gbase, voff) do { _Pragma("unroll") for (int _i = 0; _i < 2; ++_i) \
;         __builtin_amdgcn_global_load_lds((const unsigned*)((const char*)(gbase) + (voff)[_i]), (PG8_LAS unsigned*)(lds + (bufoff) + ldsw + _i * 8192), 16, 0, 0); } while (0)
; #define PG8_BAR __builtin_amdgcn_s_barrier()
; template <class Epi, class Sched, bool ALIGN_EPI = false, bool SP2 = false>
; __device__ __forceinline__ void gemm_phase(PG8_LAS unsigned char* lds, const Gemm g, const Sched& S, const Epi& E) {
;     ...
;         const bool has_next = S.next(ui + 1, nxt);
;         const char* nA = has_next ? (const char*)g.A + (size_t)nxt.pm * tstep : cA; const char* nB = has_next ? (const char*)g.Bt + (size_t)nxt.pn * tstep : cB;
;         for (int t = 0; t < nt; t += 2) {
;             const bool last = (t == nt - 2);
;             const char* a1 = cA + (size_t)(t + 1) * kstep;
;             const char* a2 = last ? nA : cA + (size_t)(t + 2) * kstep; const char* b2 = last ? nB : cB + (size_t)(t + 2) * kstep;
;             const char* a3 = a2 + kstep; const char* b3 = b2 + kstep;
;             if (last && has_next) S.a_ready(nxt);
;             if constexpr (SP2) {
;             PG8_LDB(B0, 0, 0); PG8_LDB(B1, 0, 1); PG8_SCHED; PG8_LDA(At, 0, 0); PG8_STAGE(PG8_SA(1, 1), a1 + hstep, voffA);
;             PG8_WAIT_V(8); PG8_WAIT_L(0); PG8_BAR; PG8_MMA(0, 0, At, B0); PG8_MMA(0, 1, At, B1); PG8_BAR; PG8_SCHED;
;     __device__ __forceinline__ void operator()(const f32x4 (&acc)[2][2][4][2], const pg8::Unit& u, int wr, int wc, int fr, int fq) const {
;         const int row0 = u.pm * 256 + wr * 64 + fr, col = u.pn * 128 + wc * 32 + 8 * fq;
; #pragma unroll
;         for (int ai = 0; ai < 2; ++ai)
; #pragma unroll
;             for (int m = 0; m < 4; ++m) {
;                 const int row = row0 + ai * 128 + m * 16;
;                 const float rs = sumsq ? rsqrtf(sumsq[row] * (1.f / 1024.f) + EPS) : 1.f;
;                 float o[8];
; #pragma unroll
;                 for (int n = 0; n < 2; ++n)
; #pragma unroll
;                     for (int e = 0; e < 4; ++e) { const float g = acc[ai][0][m][n][e] * rs, up = acc[ai][1][m][n][e] * rs; o[4 * n + e] = silu_f(g) * up; }
;                 u32x4 w; w.x = pk2(o[0], o[1]); w.y = pk2(o[2], o[3]); w.z = pk2(o[4], o[5]); w.w = pk2(o[6], o[7]);
;                 *(u32x4*)(H + (size_t)row * DFF + col) = w;
.LBB0_191:
	s_ashr_i32 s15, s14, 31
	s_lshl_b64 s[16:17], s[14:15], 19
	v_readlane_b32 s18, v235, 31
	v_readlane_b32 s19, v235, 32
	s_add_u32 s16, s18, s16
	s_addc_u32 s17, s19, s17
	s_and_b64 s[18:19], s[0:1], exec
	s_cselect_b32 s15, s17, s23
	s_cselect_b32 s50, s16, s22
	s_ashr_i32 s9, s8, 31
	s_lshl_b64 s[18:19], s[8:9], 19
	s_add_u32 s18, s33, s18
	s_addc_u32 s19, s34, s19
	s_and_b64 s[30:31], s[0:1], exec
	s_cselect_b32 s9, s19, s25
	s_cselect_b32 s51, s18, s24
	s_add_u32 s22, s22, 0x40080
	s_addc_u32 s23, s23, 0
	s_add_u32 s52, s24, 0x100
	s_addc_u32 s53, s25, 0
	s_mov_b32 s54, -2
	s_cmp_eq_u32 s98, 0
	s_cbranch_scc1 .Lp1_plain
	ds_read_b128 v[150:153], v147
	ds_read_b128 v[154:157], v147 offset:1024
	ds_read_b128 v[158:161], v147 offset:2048
	ds_read_b128 v[162:165], v147 offset:3072
	ds_read_b128 v[166:169], v148
	ds_read_b128 v[170:173], v148 offset:1024
	ds_read_b128 v[174:177], v148 offset:2048
	ds_read_b128 v[178:181], v148 offset:3072
	s_add_u32 s24, s22, 0xfffc0080
	s_addc_u32 s25, s23, -1
	s_cmp_eq_u32 s54, 12
	s_cselect_b32 s31, s15, s25
	s_cselect_b32 s30, s50, s24
	s_cselect_b32 s25, s9, s53
	s_cselect_b32 s24, s51, s52
	v_lshl_add_u64 v[186:187], s[22:23], 0, v[136:137]
	s_add_i32 m0, s21, 0xc000
	ds_read_b128 v[182:185], v149
	ds_read_b128 v[192:195], v149 offset:1024
	ds_read_b128 v[196:199], v149 offset:2048
	ds_read_b128 v[200:203], v149 offset:3072
	ds_read_b128 v[204:207], v149 offset:4096
	ds_read_b128 v[208:211], v149 offset:5120
	ds_read_b128 v[212:215], v149 offset:6144
	ds_read_b128 v[216:219], v149 offset:7168
	global_load_lds_dwordx4 v[186:187], off
	v_lshl_add_u64 v[186:187], s[22:23], 0, v[138:139]
	s_add_i32 m0, s21, 0xe000
	s_nop 0
	global_load_lds_dwordx4 v[186:187], off
	s_nop 1
	v_add_f32_e32 v96, 1.0, v102
	v_rcp_f32_e32 v96, v96
	v_add_f32_e32 v97, 1.0, v103
	v_rcp_f32_e32 v97, v97
	v_or_b32_e32 v98, 32, v228
	v_mul_f32_e32 v92, v92, v96
	v_mul_f32_e32 v84, v92, v84
	v_mul_f32_e32 v92, v93, v97
	v_mul_f32_e32 v93, 0xbfb8aa3b, v94
	v_exp_f32_e32 v93, v93
	v_mul_f32_e32 v96, 0xbfb8aa3b, v95
	v_exp_f32_e32 v96, v96
	v_mul_f32_e32 v85, v92, v85
	v_add_f32_e32 v92, 1.0, v93
	v_rcp_f32_e32 v92, v92
	v_add_f32_e32 v93, 1.0, v96
	v_mul_f32_e32 v96, 0xbfb8aa3b, v88
	v_rcp_f32_e32 v93, v93
	v_exp_f32_e32 v96, v96
	v_mul_f32_e32 v92, v94, v92
	v_mul_f32_e32 v86, v92, v86
	v_mul_f32_e32 v92, v95, v93
	v_add_f32_e32 v93, 1.0, v96
	v_rcp_f32_e32 v93, v93
	v_mul_f32_e32 v94, 0xbfb8aa3b, v89
	v_exp_f32_e32 v94, v94
	v_mul_f32_e32 v87, v92, v87
	v_mul_f32_e32 v88, v88, v93
	v_mul_f32_e32 v88, v88, v80
	v_add_f32_e32 v80, 1.0, v94
	v_mul_f32_e32 v92, 0xbfb8aa3b, v90
	v_rcp_f32_e32 v80, v80
	v_exp_f32_e32 v92, v92
	v_mul_f32_e32 v93, 0xbfb8aa3b, v91
	v_exp_f32_e32 v93, v93
	v_mul_f32_e32 v80, v89, v80
	v_add_f32_e32 v89, 1.0, v92
	v_rcp_f32_e32 v89, v89
	v_add_f32_e32 v92, 1.0, v93
	v_rcp_f32_e32 v92, v92
	v_mul_f32_e32 v93, v80, v81
	v_mul_f32_e32 v80, v90, v89
	v_mul_f32_e32 v89, v80, v82
	v_mul_f32_e32 v80, v91, v92
	v_mul_f32_e32 v83, v80, v83
	v_cvt_pk_bf16_f32 v80, v84, v85
	v_cvt_pk_bf16_f32 v81, v86, v87
	v_mul_f32_e32 v86, 0xbfb8aa3b, v76
	v_exp_f32_e32 v86, v86
	v_mul_f32_e32 v87, 0xbfb8aa3b, v77
	v_exp_f32_e32 v87, v87
	v_mad_i64_i32 v[84:85], s[100:101], v98, s48, v[112:113]
	v_lshl_add_u64 v[84:85], v[84:85], 0, v[114:115]
	v_cvt_pk_bf16_f32 v82, v88, v93
	v_cvt_pk_bf16_f32 v83, v89, v83
	global_store_dwordx4 v[84:85], v[80:83], off
	s_nop 1
	v_add_f32_e32 v80, 1.0, v86
	v_rcp_f32_e32 v80, v80
	v_add_f32_e32 v81, 1.0, v87
	v_rcp_f32_e32 v81, v81
	v_or_b32_e32 v82, 48, v228
	v_mul_f32_e32 v76, v76, v80
	v_mul_f32_e32 v68, v76, v68
	v_mul_f32_e32 v76, v77, v81
	v_mul_f32_e32 v77, 0xbfb8aa3b, v78
	v_exp_f32_e32 v77, v77
	v_mul_f32_e32 v80, 0xbfb8aa3b, v79
	v_exp_f32_e32 v80, v80
	v_mul_f32_e32 v69, v76, v69
	v_add_f32_e32 v76, 1.0, v77
	v_rcp_f32_e32 v76, v76
	v_add_f32_e32 v77, 1.0, v80
	v_mul_f32_e32 v80, 0xbfb8aa3b, v72
	v_rcp_f32_e32 v77, v77
	v_exp_f32_e32 v80, v80
	v_mul_f32_e32 v76, v78, v76
	v_mul_f32_e32 v70, v76, v70
	v_mul_f32_e32 v76, v79, v77
	v_add_f32_e32 v77, 1.0, v80
	v_rcp_f32_e32 v77, v77
	v_mul_f32_e32 v78, 0xbfb8aa3b, v73
	v_exp_f32_e32 v78, v78
	v_mul_f32_e32 v71, v76, v71
	v_mul_f32_e32 v72, v72, v77
	v_mul_f32_e32 v72, v72, v64
	v_add_f32_e32 v64, 1.0, v78
	v_mul_f32_e32 v76, 0xbfb8aa3b, v74
	v_rcp_f32_e32 v64, v64
	v_exp_f32_e32 v76, v76
	v_mul_f32_e32 v77, 0xbfb8aa3b, v75
	v_exp_f32_e32 v77, v77
	v_mul_f32_e32 v64, v73, v64
	v_add_f32_e32 v73, 1.0, v76
	v_rcp_f32_e32 v73, v73
	v_add_f32_e32 v76, 1.0, v77
	v_rcp_f32_e32 v76, v76
	v_mul_f32_e32 v77, v64, v65
	v_mul_f32_e32 v64, v74, v73
	v_mul_f32_e32 v73, v64, v66
	v_mul_f32_e32 v64, v75, v76
	v_mul_f32_e32 v67, v64, v67
	v_cvt_pk_bf16_f32 v64, v68, v69
	v_cvt_pk_bf16_f32 v65, v70, v71
	v_mul_f32_e32 v70, 0xbfb8aa3b, v60
	v_exp_f32_e32 v70, v70
	v_mul_f32_e32 v71, 0xbfb8aa3b, v61
	v_exp_f32_e32 v71, v71
	v_mad_i64_i32 v[68:69], s[100:101], v82, s48, v[112:113]
	v_lshl_add_u64 v[68:69], v[68:69], 0, v[114:115]
	v_cvt_pk_bf16_f32 v66, v72, v77
	v_cvt_pk_bf16_f32 v67, v73, v67
	global_store_dwordx4 v[68:69], v[64:67], off
	s_nop 1
	v_add_f32_e32 v64, 1.0, v70
	v_rcp_f32_e32 v64, v64
	v_add_f32_e32 v65, 1.0, v71
	v_rcp_f32_e32 v65, v65
	v_add_u32_e32 v66, 0x80, v228
	v_mul_f32_e32 v60, v60, v64
	v_mul_f32_e32 v52, v60, v52
	v_mul_f32_e32 v60, v61, v65
	v_mul_f32_e32 v61, 0xbfb8aa3b, v62
	v_exp_f32_e32 v61, v61
	v_mul_f32_e32 v64, 0xbfb8aa3b, v63
	v_exp_f32_e32 v64, v64
	v_mul_f32_e32 v53, v60, v53
	v_add_f32_e32 v60, 1.0, v61
	v_rcp_f32_e32 v60, v60
	v_add_f32_e32 v61, 1.0, v64
	v_mul_f32_e32 v64, 0xbfb8aa3b, v56
	v_rcp_f32_e32 v61, v61
; #define PG8_MMA(ai, bj, At, Bt) do { __builtin_amdgcn_s_setprio(1); _Pragma("unroll") for (int m = 0; m < 4; ++m) _Pragma("unroll") for (int n = 0; n < 2; ++n) _Pragma("unroll") for (int k = 0; k < 2; ++k) \
;         acc[ai][bj][m][n] = __builtin_amdgcn_mfma_f32_16x16x32_bf16(Bt[n][k], At[m][k], acc[ai][bj][m][n], 0, 0, 0); __builtin_amdgcn_s_setprio(0); } while (0)
; #define PG8_WAIT_V(n) asm volatile("s_waitcnt vmcnt(" #n ")" ::: "memory")
; #define PG8_WAIT_L(n) asm volatile("s_waitcnt lgkmcnt(" #n ")" ::: "memory")
; #define PG8_BAR __builtin_amdgcn_s_barrier()
; #define PG8_SCHED __builtin_amdgcn_sched_barrier(0)
; __device__ __forceinline__ unsigned pk2(float lo, float hi) { return pg8::cvt_pk_bf16(lo, hi); }
; __device__ __forceinline__ float silu_f(float x) { return x * sigmoid_f(x); }
; template <class Epi, class Sched, bool ALIGN_EPI = false, bool SP2 = false>
; __device__ __forceinline__ void gemm_phase(PG8_LAS unsigned char* lds, const Gemm g, const Sched& S, const Epi& E) {
;     ...
;             PG8_WAIT_V(8); PG8_WAIT_L(0); PG8_BAR; PG8_MMA(0, 0, At, B0); PG8_MMA(0, 1, At, B1); PG8_BAR; PG8_SCHED;
;     __device__ __forceinline__ void operator()(const f32x4 (&acc)[2][2][4][2], const pg8::Unit& u, int wr, int wc, int fr, int fq) const {
;         const int row0 = u.pm * 256 + wr * 64 + fr, col = u.pn * 128 + wc * 32 + 8 * fq;
; #pragma unroll
;         for (int ai = 0; ai < 2; ++ai)
; #pragma unroll
;             for (int m = 0; m < 4; ++m) {
;                 const int row = row0 + ai * 128 + m * 16;
;                 const float rs = sumsq ? rsqrtf(sumsq[row] * (1.f / 1024.f) + EPS) : 1.f;
;                 float o[8];
; #pragma unroll
;                 for (int n = 0; n < 2; ++n)
; #pragma unroll
;                     for (int e = 0; e < 4; ++e) { const float g = acc[ai][0][m][n][e] * rs, up = acc[ai][1][m][n][e] * rs; o[4 * n + e] = silu_f(g) * up; }
;                 u32x4 w; w.x = pk2(o[0], o[1]); w.y = pk2(o[2], o[3]); w.z = pk2(o[4], o[5]); w.w = pk2(o[6], o[7]);
;                 *(u32x4*)(H + (size_t)row * DFF + col) = w;
	v_exp_f32_e32 v64, v64
	v_mul_f32_e32 v60, v62, v60
	v_mul_f32_e32 v54, v60, v54
	v_mul_f32_e32 v60, v63, v61
	v_add_f32_e32 v61, 1.0, v64
	v_rcp_f32_e32 v61, v61
	v_mul_f32_e32 v62, 0xbfb8aa3b, v57
	v_exp_f32_e32 v62, v62
	v_mul_f32_e32 v55, v60, v55
	v_mul_f32_e32 v56, v56, v61
	v_mul_f32_e32 v56, v56, v48
	v_add_f32_e32 v48, 1.0, v62
	v_mul_f32_e32 v60, 0xbfb8aa3b, v58
	v_rcp_f32_e32 v48, v48
	v_exp_f32_e32 v60, v60
	v_mul_f32_e32 v61, 0xbfb8aa3b, v59
	v_exp_f32_e32 v61, v61
	v_mul_f32_e32 v48, v57, v48
	v_add_f32_e32 v57, 1.0, v60
	v_rcp_f32_e32 v57, v57
	v_add_f32_e32 v60, 1.0, v61
	v_rcp_f32_e32 v60, v60
	v_mul_f32_e32 v61, v48, v49
	v_mul_f32_e32 v48, v58, v57
	v_mul_f32_e32 v57, v48, v50
	v_mul_f32_e32 v48, v59, v60
	v_mul_f32_e32 v51, v48, v51
	v_cvt_pk_bf16_f32 v48, v52, v53
	v_cvt_pk_bf16_f32 v49, v54, v55
	v_mul_f32_e32 v54, 0xbfb8aa3b, v44
	v_exp_f32_e32 v54, v54
	v_mul_f32_e32 v55, 0xbfb8aa3b, v45
	v_exp_f32_e32 v55, v55
	v_mad_i64_i32 v[52:53], s[100:101], v66, s48, v[112:113]
	v_lshl_add_u64 v[52:53], v[52:53], 0, v[114:115]
	v_cvt_pk_bf16_f32 v50, v56, v61
	v_cvt_pk_bf16_f32 v51, v57, v51
	global_store_dwordx4 v[52:53], v[48:51], off
	s_nop 1
	v_add_f32_e32 v48, 1.0, v54
	v_rcp_f32_e32 v48, v48
	v_add_f32_e32 v49, 1.0, v55
	v_rcp_f32_e32 v49, v49
	v_add_u32_e32 v50, 0x90, v228
	v_mul_f32_e32 v44, v44, v48
	v_mul_f32_e32 v36, v44, v36
	v_mul_f32_e32 v44, v45, v49
	v_mul_f32_e32 v45, 0xbfb8aa3b, v46
	v_exp_f32_e32 v45, v45
	v_mul_f32_e32 v48, 0xbfb8aa3b, v47
	v_exp_f32_e32 v48, v48
	v_mul_f32_e32 v37, v44, v37
	v_add_f32_e32 v44, 1.0, v45
	v_rcp_f32_e32 v44, v44
	v_add_f32_e32 v45, 1.0, v48
	v_mul_f32_e32 v48, 0xbfb8aa3b, v40
	v_rcp_f32_e32 v45, v45
	v_exp_f32_e32 v48, v48
	v_mul_f32_e32 v44, v46, v44
	v_mul_f32_e32 v38, v44, v38
	v_mul_f32_e32 v44, v47, v45
	v_add_f32_e32 v45, 1.0, v48
	v_rcp_f32_e32 v45, v45
	v_mul_f32_e32 v46, 0xbfb8aa3b, v41
	v_exp_f32_e32 v46, v46
	v_mul_f32_e32 v39, v44, v39
	v_mul_f32_e32 v40, v40, v45
	v_mul_f32_e32 v40, v40, v32
	v_add_f32_e32 v32, 1.0, v46
	v_mul_f32_e32 v44, 0xbfb8aa3b, v42
	v_rcp_f32_e32 v32, v32
	v_exp_f32_e32 v44, v44
	v_mul_f32_e32 v45, 0xbfb8aa3b, v43
	v_exp_f32_e32 v45, v45
	v_mul_f32_e32 v32, v41, v32
	v_add_f32_e32 v41, 1.0, v44
	v_rcp_f32_e32 v41, v41
	v_add_f32_e32 v44, 1.0, v45
	v_rcp_f32_e32 v44, v44
	v_mul_f32_e32 v45, v32, v33
	v_mul_f32_e32 v32, v42, v41
	v_mul_f32_e32 v41, v32, v34
	v_mul_f32_e32 v32, v43, v44
	v_mul_f32_e32 v35, v32, v35
	v_cvt_pk_bf16_f32 v32, v36, v37
	v_cvt_pk_bf16_f32 v33, v38, v39
	v_mul_f32_e32 v38, 0xbfb8aa3b, v28
	v_exp_f32_e32 v38, v38
	v_mul_f32_e32 v39, 0xbfb8aa3b, v29
	v_exp_f32_e32 v39, v39
	v_mad_i64_i32 v[36:37], s[100:101], v50, s48, v[112:113]
	v_lshl_add_u64 v[36:37], v[36:37], 0, v[114:115]
	v_cvt_pk_bf16_f32 v34, v40, v45
	v_cvt_pk_bf16_f32 v35, v41, v35
	global_store_dwordx4 v[36:37], v[32:35], off
	s_nop 1
	v_add_f32_e32 v32, 1.0, v38
	v_rcp_f32_e32 v32, v32
	v_add_f32_e32 v33, 1.0, v39
	v_rcp_f32_e32 v33, v33
	v_add_u32_e32 v34, 0xa0, v228
	v_mul_f32_e32 v28, v28, v32
	v_mul_f32_e32 v20, v28, v20
	v_mul_f32_e32 v28, v29, v33
	v_mul_f32_e32 v29, 0xbfb8aa3b, v30
	v_exp_f32_e32 v29, v29
	v_mul_f32_e32 v32, 0xbfb8aa3b, v31
	v_exp_f32_e32 v32, v32
	v_mul_f32_e32 v21, v28, v21
	v_add_f32_e32 v28, 1.0, v29
	v_rcp_f32_e32 v28, v28
	v_add_f32_e32 v29, 1.0, v32
	v_mul_f32_e32 v32, 0xbfb8aa3b, v24
	v_rcp_f32_e32 v29, v29
	v_exp_f32_e32 v32, v32
	v_mul_f32_e32 v28, v30, v28
	v_mul_f32_e32 v22, v28, v22
	v_mul_f32_e32 v28, v31, v29
	v_add_f32_e32 v29, 1.0, v32
	v_rcp_f32_e32 v29, v29
	v_mul_f32_e32 v30, 0xbfb8aa3b, v25
	v_exp_f32_e32 v30, v30
	v_mul_f32_e32 v23, v28, v23
	v_mul_f32_e32 v24, v24, v29
	v_mul_f32_e32 v24, v24, v16
	v_add_f32_e32 v16, 1.0, v30
	v_mul_f32_e32 v28, 0xbfb8aa3b, v26
	v_rcp_f32_e32 v16, v16
	v_exp_f32_e32 v28, v28
	v_mul_f32_e32 v29, 0xbfb8aa3b, v27
	v_exp_f32_e32 v29, v29
	v_mul_f32_e32 v16, v25, v16
	v_add_f32_e32 v25, 1.0, v28
	v_rcp_f32_e32 v25, v25
	v_add_f32_e32 v28, 1.0, v29
	v_rcp_f32_e32 v28, v28
	v_mul_f32_e32 v29, v16, v17
	v_mul_f32_e32 v16, v26, v25
	v_mul_f32_e32 v25, v16, v18
	v_mul_f32_e32 v16, v27, v28
	v_mul_f32_e32 v19, v16, v19
	v_cvt_pk_bf16_f32 v16, v20, v21
	v_cvt_pk_bf16_f32 v17, v22, v23
	v_mul_f32_e32 v22, 0xbfb8aa3b, v12
	v_exp_f32_e32 v22, v22
	v_mul_f32_e32 v23, 0xbfb8aa3b, v13
	v_exp_f32_e32 v23, v23
	v_mad_i64_i32 v[20:21], s[100:101], v34, s48, v[112:113]
	v_lshl_add_u64 v[20:21], v[20:21], 0, v[114:115]
	v_cvt_pk_bf16_f32 v18, v24, v29
	v_cvt_pk_bf16_f32 v19, v25, v19
	global_store_dwordx4 v[20:21], v[16:19], off
	s_nop 1
	v_add_f32_e32 v16, 1.0, v22
	v_rcp_f32_e32 v16, v16
	v_add_f32_e32 v17, 1.0, v23
	v_rcp_f32_e32 v17, v17
	v_add_u32_e32 v18, 0xb0, v228
	v_mul_f32_e32 v12, v12, v16
	v_mul_f32_e32 v4, v12, v4
	v_mul_f32_e32 v12, v13, v17
	v_mul_f32_e32 v13, 0xbfb8aa3b, v14
	v_exp_f32_e32 v13, v13
	v_mul_f32_e32 v16, 0xbfb8aa3b, v15
	v_exp_f32_e32 v16, v16
	v_mul_f32_e32 v5, v12, v5
	v_add_f32_e32 v12, 1.0, v13
	v_rcp_f32_e32 v12, v12
	v_add_f32_e32 v13, 1.0, v16
	v_mul_f32_e32 v16, 0xbfb8aa3b, v8
	v_rcp_f32_e32 v13, v13
	v_exp_f32_e32 v16, v16
	v_mul_f32_e32 v12, v14, v12
	v_mul_f32_e32 v6, v12, v6
	v_mul_f32_e32 v12, v15, v13
	v_add_f32_e32 v13, 1.0, v16
	v_rcp_f32_e32 v13, v13
	v_mul_f32_e32 v14, 0xbfb8aa3b, v9
	v_exp_f32_e32 v14, v14
	v_mul_f32_e32 v7, v12, v7
	v_mul_f32_e32 v8, v8, v13
	v_mul_f32_e32 v8, v8, v0
	v_add_f32_e32 v0, 1.0, v14
	v_mul_f32_e32 v12, 0xbfb8aa3b, v10
	v_rcp_f32_e32 v0, v0
	v_exp_f32_e32 v12, v12
	v_mul_f32_e32 v13, 0xbfb8aa3b, v11
	v_exp_f32_e32 v13, v13
	v_mul_f32_e32 v0, v9, v0
	v_add_f32_e32 v9, 1.0, v12
	v_rcp_f32_e32 v9, v9
	v_add_f32_e32 v12, 1.0, v13
	v_rcp_f32_e32 v12, v12
	v_mul_f32_e32 v13, v0, v1
	v_mul_f32_e32 v0, v10, v9
	v_mul_f32_e32 v9, v0, v2
	v_mul_f32_e32 v0, v11, v12
	v_mul_f32_e32 v3, v0, v3
	v_cvt_pk_bf16_f32 v0, v4, v5
	v_mad_i64_i32 v[4:5], s[100:101], v18, s48, v[112:113]
	v_lshl_add_u64 v[4:5], v[4:5], 0, v[114:115]
	v_cvt_pk_bf16_f32 v1, v6, v7
	v_cvt_pk_bf16_f32 v2, v8, v13
	v_cvt_pk_bf16_f32 v3, v9, v3
	global_store_dwordx4 v[4:5], v[0:3], off
	s_waitcnt vmcnt(16)
	s_waitcnt lgkmcnt(0)
	s_barrier
; #define PG8_STAGE(bufoff, gbase, voff) do { _Pragma("unroll") for (int _i = 0; _i < 2; ++_i) \
;         __builtin_amdgcn_global_load_lds((const unsigned*)((const char*)(gbase) + (voff)[_i]), (PG8_LAS unsigned*)(lds + (bufoff) + ldsw + _i * 8192), 16, 0, 0); } while (0)
; #define PG8_LDA(dst, b, h) do { _Pragma("unroll") for (int m = 0; m < 4; ++m) _Pragma("unroll") for (int k = 0; k < 2; ++k) dst[m][k] = *(const PG8_LAS bf16x8*)(lds + PG8_SA(b, h) + aoff + m * 2048 + k * 1024); } while (0)
; #define PG8_LDB(dst, b, h) do { _Pragma("unroll") for (int n = 0; n < 2; ++n) _Pragma("unroll") for (int k = 0; k < 2; ++k) dst[n][k] = *(const PG8_LAS bf16x8*)(lds + PG8_SB(b, h) + boff + n * 2048 + k * 1024); } while (0)
; #define PG8_MMA(ai, bj, At, Bt) do { __builtin_amdgcn_s_setprio(1); _Pragma("unroll") for (int m = 0; m < 4; ++m) _Pragma("unroll") for (int n = 0; n < 2; ++n) _Pragma("unroll") for (int k = 0; k < 2; ++k) \
;         acc[ai][bj][m][n] = __builtin_amdgcn_mfma_f32_16x16x32_bf16(Bt[n][k], At[m][k], acc[ai][bj][m][n], 0, 0, 0); __builtin_amdgcn_s_setprio(0); } while (0)
; #define PG8_WAIT_V(n) asm volatile("s_waitcnt vmcnt(" #n ")" ::: "memory")
; #define PG8_WAIT_L(n) asm volatile("s_waitcnt lgkmcnt(" #n ")" ::: "memory")
; #define PG8_BAR __builtin_amdgcn_s_barrier()
; #define PG8_SCHED __builtin_amdgcn_sched_barrier(0)
; template <class Epi, class Sched, bool ALIGN_EPI = false, bool SP2 = false>
; __device__ __forceinline__ void gemm_phase(PG8_LAS unsigned char* lds, const Gemm g, const Sched& S, const Epi& E) {
;     ...
;             PG8_LDB(B0, 0, 0); PG8_LDB(B1, 0, 1); PG8_SCHED; PG8_LDA(At, 0, 0); PG8_STAGE(PG8_SA(1, 1), a1 + hstep, voffA);
;             PG8_WAIT_V(8); PG8_WAIT_L(0); PG8_BAR; PG8_MMA(0, 0, At, B0); PG8_MMA(0, 1, At, B1); PG8_BAR; PG8_SCHED;
;             PG8_LDA(At, 0, 1); PG8_STAGE(PG8_SB(0, 0), b2, voffB); PG8_STAGE(PG8_SB(0, 1), b2 + hstep, voffB); PG8_STAGE(PG8_SA(0, 0), a2, voffA);
;             PG8_WAIT_V(8); PG8_WAIT_L(0); PG8_BAR; PG8_MMA(1, 0, At, B0); PG8_MMA(1, 1, At, B1); PG8_BAR; PG8_SCHED;
	s_setprio 1
	v_mfma_f32_16x16x32_bf16 v[124:127], v[150:153], v[182:185], 0
	v_mfma_f32_16x16x32_bf16 v[120:123], v[158:161], v[182:185], 0
	v_mfma_f32_16x16x32_bf16 v[108:111], v[150:153], v[196:199], 0
	v_mfma_f32_16x16x32_bf16 v[104:107], v[158:161], v[196:199], 0
	v_mfma_f32_16x16x32_bf16 v[92:95], v[150:153], v[204:207], 0
	v_mfma_f32_16x16x32_bf16 v[88:91], v[158:161], v[204:207], 0
	v_mfma_f32_16x16x32_bf16 v[76:79], v[150:153], v[212:215], 0
	v_mfma_f32_16x16x32_bf16 v[72:75], v[158:161], v[212:215], 0
	v_mfma_f32_16x16x32_bf16 v[124:127], v[154:157], v[192:195], v[124:127]
	v_mfma_f32_16x16x32_bf16 v[120:123], v[162:165], v[192:195], v[120:123]
	v_mfma_f32_16x16x32_bf16 v[108:111], v[154:157], v[200:203], v[108:111]
	v_mfma_f32_16x16x32_bf16 v[104:107], v[162:165], v[200:203], v[104:107]
	v_mfma_f32_16x16x32_bf16 v[92:95], v[154:157], v[208:211], v[92:95]
	v_mfma_f32_16x16x32_bf16 v[88:91], v[162:165], v[208:211], v[88:91]
	v_mfma_f32_16x16x32_bf16 v[76:79], v[154:157], v[216:219], v[76:79]
	v_mfma_f32_16x16x32_bf16 v[72:75], v[162:165], v[216:219], v[72:75]
	v_mfma_f32_16x16x32_bf16 v[116:119], v[166:169], v[182:185], 0
	v_mfma_f32_16x16x32_bf16 v[112:115], v[174:177], v[182:185], 0
	v_mfma_f32_16x16x32_bf16 v[100:103], v[166:169], v[196:199], 0
	v_mfma_f32_16x16x32_bf16 v[96:99], v[174:177], v[196:199], 0
	v_mfma_f32_16x16x32_bf16 v[84:87], v[166:169], v[204:207], 0
	v_mfma_f32_16x16x32_bf16 v[80:83], v[174:177], v[204:207], 0
	v_mfma_f32_16x16x32_bf16 v[68:71], v[166:169], v[212:215], 0
	v_mfma_f32_16x16x32_bf16 v[64:67], v[174:177], v[212:215], 0
	v_mfma_f32_16x16x32_bf16 v[116:119], v[170:173], v[192:195], v[116:119]
	v_mfma_f32_16x16x32_bf16 v[112:115], v[178:181], v[192:195], v[112:115]
	v_mfma_f32_16x16x32_bf16 v[100:103], v[170:173], v[200:203], v[100:103]
	v_mfma_f32_16x16x32_bf16 v[96:99], v[178:181], v[200:203], v[96:99]
	v_mfma_f32_16x16x32_bf16 v[84:87], v[170:173], v[208:211], v[84:87]
	v_mfma_f32_16x16x32_bf16 v[80:83], v[178:181], v[208:211], v[80:83]
	v_mfma_f32_16x16x32_bf16 v[68:71], v[170:173], v[216:219], v[68:71]
	v_mfma_f32_16x16x32_bf16 v[64:67], v[178:181], v[216:219], v[64:67]
	s_setprio 0
	s_barrier
	s_add_i32 s55, s46, s35
	v_lshl_add_u64 v[186:187], s[24:25], 0, v[132:133]
	s_mov_b32 m0, s55
	ds_read_b128 v[182:185], v149 offset:16384
	ds_read_b128 v[192:195], v149 offset:17408
	ds_read_b128 v[196:199], v149 offset:18432
	ds_read_b128 v[200:203], v149 offset:19456
	ds_read_b128 v[204:207], v149 offset:20480
	ds_read_b128 v[208:211], v149 offset:21504
	ds_read_b128 v[212:215], v149 offset:22528
	ds_read_b128 v[216:219], v149 offset:23552
	global_load_lds_dwordx4 v[186:187], off
	s_add_i32 m0, s55, 0x2000
	s_add_u32 s56, s24, 0x40000
	v_lshl_add_u64 v[220:221], s[24:25], 0, v[128:129]
	s_addc_u32 s57, s25, 0
	s_add_i32 s55, s47, s35
	global_load_lds_dwordx4 v[220:221], off
	v_lshl_add_u64 v[222:223], s[56:57], 0, v[132:133]
	s_mov_b32 m0, s55
	v_lshl_add_u64 v[224:225], s[30:31], 0, v[130:131]
	global_load_lds_dwordx4 v[222:223], off
	v_lshl_add_u64 v[222:223], s[56:57], 0, v[128:129]
	s_add_i32 m0, s55, 0x2000
	s_nop 0
	global_load_lds_dwordx4 v[222:223], off
	v_lshl_add_u64 v[222:223], s[30:31], 0, v[134:135]
	s_mov_b32 m0, s21
	s_nop 0
	global_load_lds_dwordx4 v[222:223], off
	s_mov_b32 m0, s38
	s_nop 0
	global_load_lds_dwordx4 v[224:225], off
	s_waitcnt vmcnt(16)
	s_waitcnt lgkmcnt(0)
	s_barrier
	s_setprio 1
	v_mfma_f32_16x16x32_bf16 v[60:63], v[150:153], v[182:185], 0
	v_mfma_f32_16x16x32_bf16 v[56:59], v[158:161], v[182:185], 0
	v_mfma_f32_16x16x32_bf16 v[44:47], v[150:153], v[196:199], 0
	v_mfma_f32_16x16x32_bf16 v[40:43], v[158:161], v[196:199], 0
	v_mfma_f32_16x16x32_bf16 v[28:31], v[150:153], v[204:207], 0
	v_mfma_f32_16x16x32_bf16 v[24:27], v[158:161], v[204:207], 0
	v_mfma_f32_16x16x32_bf16 v[12:15], v[150:153], v[212:215], 0
	v_mfma_f32_16x16x32_bf16 v[8:11], v[158:161], v[212:215], 0
	v_mfma_f32_16x16x32_bf16 v[60:63], v[154:157], v[192:195], v[60:63]
	v_mfma_f32_16x16x32_bf16 v[56:59], v[162:165], v[192:195], v[56:59]
	v_mfma_f32_16x16x32_bf16 v[44:47], v[154:157], v[200:203], v[44:47]
	v_mfma_f32_16x16x32_bf16 v[40:43], v[162:165], v[200:203], v[40:43]
	v_mfma_f32_16x16x32_bf16 v[28:31], v[154:157], v[208:211], v[28:31]
	v_mfma_f32_16x16x32_bf16 v[24:27], v[162:165], v[208:211], v[24:27]
	v_mfma_f32_16x16x32_bf16 v[12:15], v[154:157], v[216:219], v[12:15]
	v_mfma_f32_16x16x32_bf16 v[8:11], v[162:165], v[216:219], v[8:11]
	v_mfma_f32_16x16x32_bf16 v[52:55], v[166:169], v[182:185], 0
	v_mfma_f32_16x16x32_bf16 v[48:51], v[174:177], v[182:185], 0
	v_mfma_f32_16x16x32_bf16 v[36:39], v[166:169], v[196:199], 0
	v_mfma_f32_16x16x32_bf16 v[32:35], v[174:177], v[196:199], 0
	v_mfma_f32_16x16x32_bf16 v[20:23], v[166:169], v[204:207], 0
	v_mfma_f32_16x16x32_bf16 v[16:19], v[174:177], v[204:207], 0
	v_mfma_f32_16x16x32_bf16 v[4:7], v[166:169], v[212:215], 0
	v_mfma_f32_16x16x32_bf16 v[0:3], v[174:177], v[212:215], 0
	v_mfma_f32_16x16x32_bf16 v[52:55], v[170:173], v[192:195], v[52:55]
	v_mfma_f32_16x16x32_bf16 v[48:51], v[178:181], v[192:195], v[48:51]
	v_mfma_f32_16x16x32_bf16 v[36:39], v[170:173], v[200:203], v[36:39]
	v_mfma_f32_16x16x32_bf16 v[32:35], v[178:181], v[200:203], v[32:35]
	v_mfma_f32_16x16x32_bf16 v[20:23], v[170:173], v[208:211], v[20:23]
	v_mfma_f32_16x16x32_bf16 v[16:19], v[178:181], v[208:211], v[16:19]
	v_mfma_f32_16x16x32_bf16 v[4:7], v[170:173], v[216:219], v[4:7]
	v_mfma_f32_16x16x32_bf16 v[0:3], v[178:181], v[216:219], v[0:3]
	s_setprio 0
	s_barrier
; #define PG8_STAGE(bufoff, gbase, voff) do { _Pragma("unroll") for (int _i = 0; _i < 2; ++_i) \
;         __builtin_amdgcn_global_load_lds((const unsigned*)((const char*)(gbase) + (voff)[_i]), (PG8_LAS unsigned*)(lds + (bufoff) + ldsw + _i * 8192), 16, 0, 0); } while (0)
; #define PG8_LDA(dst, b, h) do { _Pragma("unroll") for (int m = 0; m < 4; ++m) _Pragma("unroll") for (int k = 0; k < 2; ++k) dst[m][k] = *(const PG8_LAS bf16x8*)(lds + PG8_SA(b, h) + aoff + m * 2048 + k * 1024); } while (0)
; #define PG8_LDB(dst, b, h) do { _Pragma("unroll") for (int n = 0; n < 2; ++n) _Pragma("unroll") for (int k = 0; k < 2; ++k) dst[n][k] = *(const PG8_LAS bf16x8*)(lds + PG8_SB(b, h) + boff + n * 2048 + k * 1024); } while (0)
; #define PG8_MMA(ai, bj, At, Bt) do { __builtin_amdgcn_s_setprio(1); _Pragma("unroll") for (int m = 0; m < 4; ++m) _Pragma("unroll") for (int n = 0; n < 2; ++n) _Pragma("unroll") for (int k = 0; k < 2; ++k) \
;         acc[ai][bj][m][n] = __builtin_amdgcn_mfma_f32_16x16x32_bf16(Bt[n][k], At[m][k], acc[ai][bj][m][n], 0, 0, 0); __builtin_amdgcn_s_setprio(0); } while (0)
; #define PG8_WAIT_V(n) asm volatile("s_waitcnt vmcnt(" #n ")" ::: "memory")
; #define PG8_WAIT_L(n) asm volatile("s_waitcnt lgkmcnt(" #n ")" ::: "memory")
; #define PG8_BAR __builtin_amdgcn_s_barrier()
; #define PG8_SCHED __builtin_amdgcn_sched_barrier(0)
; template <class Epi, class Sched, bool ALIGN_EPI = false, bool SP2 = false>
; __device__ __forceinline__ void gemm_phase(PG8_LAS unsigned char* lds, const Gemm g, const Sched& S, const Epi& E) {
;     ...
;             PG8_LDB(B0, 1, 0); PG8_LDB(B1, 1, 1); PG8_SCHED; PG8_LDA(At, 1, 0); PG8_STAGE(PG8_SA(0, 1), a2 + hstep, voffA);
;             PG8_WAIT_V(8); PG8_WAIT_L(0); PG8_BAR; PG8_MMA(0, 0, At, B0); PG8_MMA(0, 1, At, B1); PG8_BAR; PG8_SCHED;
;             PG8_LDA(At, 1, 1); PG8_STAGE(PG8_SB(1, 0), b3, voffB); PG8_STAGE(PG8_SB(1, 1), b3 + hstep, voffB); PG8_STAGE(PG8_SA(1, 0), a3, voffA);
;             PG8_WAIT_V(8); PG8_WAIT_L(0); PG8_BAR; PG8_MMA(1, 0, At, B0); PG8_MMA(1, 1, At, B1); PG8_BAR; PG8_SCHED;
	s_add_i32 s55, 0, 0x18000
	s_add_i32 s56, 0, 0x1c000
	v_add_u32_e32 v162, s55, v145
	v_add_u32_e32 v178, s56, v145
	ds_read_b128 v[150:153], v162
	ds_read_b128 v[154:157], v162 offset:1024
	ds_read_b128 v[158:161], v162 offset:2048
	ds_read_b128 v[162:165], v162 offset:3072
	ds_read_b128 v[166:169], v178
	ds_read_b128 v[170:173], v178 offset:1024
	ds_read_b128 v[174:177], v178 offset:2048
	ds_read_b128 v[178:181], v178 offset:3072
	s_add_u32 s30, s30, 0x40000
	s_addc_u32 s31, s31, 0
	s_mov_b32 m0, s39
	v_lshl_add_u64 v[226:227], s[30:31], 0, v[134:135]
	ds_read_b128 v[182:185], v149 offset:32768
	ds_read_b128 v[192:195], v149 offset:33792
	ds_read_b128 v[196:199], v149 offset:34816
	ds_read_b128 v[200:203], v149 offset:35840
	ds_read_b128 v[204:207], v149 offset:36864
	ds_read_b128 v[208:211], v149 offset:37888
	ds_read_b128 v[212:215], v149 offset:38912
	ds_read_b128 v[216:219], v149 offset:39936
	global_load_lds_dwordx4 v[226:227], off
	v_lshl_add_u64 v[226:227], s[30:31], 0, v[130:131]
	s_mov_b32 m0, s40
	s_nop 0
	global_load_lds_dwordx4 v[226:227], off
	s_waitcnt vmcnt(8)
	s_waitcnt lgkmcnt(0)
	s_barrier
	s_setprio 1
	v_mfma_f32_16x16x32_bf16 v[124:127], v[150:153], v[182:185], v[124:127]
	v_mfma_f32_16x16x32_bf16 v[120:123], v[158:161], v[182:185], v[120:123]
	v_mfma_f32_16x16x32_bf16 v[108:111], v[150:153], v[196:199], v[108:111]
	v_mfma_f32_16x16x32_bf16 v[104:107], v[158:161], v[196:199], v[104:107]
	v_mfma_f32_16x16x32_bf16 v[92:95], v[150:153], v[204:207], v[92:95]
	v_mfma_f32_16x16x32_bf16 v[88:91], v[158:161], v[204:207], v[88:91]
	v_mfma_f32_16x16x32_bf16 v[76:79], v[150:153], v[212:215], v[76:79]
	v_mfma_f32_16x16x32_bf16 v[72:75], v[158:161], v[212:215], v[72:75]
	v_mfma_f32_16x16x32_bf16 v[124:127], v[154:157], v[192:195], v[124:127]
	v_mfma_f32_16x16x32_bf16 v[120:123], v[162:165], v[192:195], v[120:123]
	v_mfma_f32_16x16x32_bf16 v[108:111], v[154:157], v[200:203], v[108:111]
	v_mfma_f32_16x16x32_bf16 v[104:107], v[162:165], v[200:203], v[104:107]
	v_mfma_f32_16x16x32_bf16 v[92:95], v[154:157], v[208:211], v[92:95]
	v_mfma_f32_16x16x32_bf16 v[88:91], v[162:165], v[208:211], v[88:91]
	v_mfma_f32_16x16x32_bf16 v[76:79], v[154:157], v[216:219], v[76:79]
	v_mfma_f32_16x16x32_bf16 v[72:75], v[162:165], v[216:219], v[72:75]
	v_mfma_f32_16x16x32_bf16 v[116:119], v[166:169], v[182:185], v[116:119]
	v_mfma_f32_16x16x32_bf16 v[112:115], v[174:177], v[182:185], v[112:115]
	v_mfma_f32_16x16x32_bf16 v[100:103], v[166:169], v[196:199], v[100:103]
	v_mfma_f32_16x16x32_bf16 v[96:99], v[174:177], v[196:199], v[96:99]
	v_mfma_f32_16x16x32_bf16 v[84:87], v[166:169], v[204:207], v[84:87]
	v_mfma_f32_16x16x32_bf16 v[80:83], v[174:177], v[204:207], v[80:83]
	v_mfma_f32_16x16x32_bf16 v[68:71], v[166:169], v[212:215], v[68:71]
	v_mfma_f32_16x16x32_bf16 v[64:67], v[174:177], v[212:215], v[64:67]
	v_mfma_f32_16x16x32_bf16 v[116:119], v[170:173], v[192:195], v[116:119]
	v_mfma_f32_16x16x32_bf16 v[112:115], v[178:181], v[192:195], v[112:115]
	v_mfma_f32_16x16x32_bf16 v[100:103], v[170:173], v[200:203], v[100:103]
	v_mfma_f32_16x16x32_bf16 v[96:99], v[178:181], v[200:203], v[96:99]
	v_mfma_f32_16x16x32_bf16 v[84:87], v[170:173], v[208:211], v[84:87]
	v_mfma_f32_16x16x32_bf16 v[80:83], v[178:181], v[208:211], v[80:83]
	v_mfma_f32_16x16x32_bf16 v[68:71], v[170:173], v[216:219], v[68:71]
	v_mfma_f32_16x16x32_bf16 v[64:67], v[178:181], v[216:219], v[64:67]
	s_setprio 0
	s_barrier
	s_add_i32 s30, s55, s35
	v_lshl_add_u64 v[186:187], v[186:187], 0, s[4:5]
	s_mov_b32 m0, s30
	ds_read_b128 v[182:185], v149 offset:49152
	ds_read_b128 v[192:195], v149 offset:50176
	ds_read_b128 v[196:199], v149 offset:51200
	ds_read_b128 v[200:203], v149 offset:52224
	ds_read_b128 v[204:207], v149 offset:53248
	ds_read_b128 v[208:211], v149 offset:54272
	ds_read_b128 v[212:215], v149 offset:55296
	ds_read_b128 v[216:219], v149 offset:56320
	global_load_lds_dwordx4 v[186:187], off
	s_add_i32 m0, s30, 0x2000
	s_add_u32 s24, s24, 0x40080
	v_lshl_add_u64 v[186:187], v[220:221], 0, s[4:5]
	s_addc_u32 s25, s25, 0
	s_add_i32 s30, s56, s35
	global_load_lds_dwordx4 v[186:187], off
	v_lshl_add_u64 v[186:187], s[24:25], 0, v[132:133]
	s_mov_b32 m0, s30
	s_nop 0
	global_load_lds_dwordx4 v[186:187], off
	v_lshl_add_u64 v[186:187], s[24:25], 0, v[128:129]
	s_add_i32 m0, s30, 0x2000
	s_nop 0
	global_load_lds_dwordx4 v[186:187], off
	v_lshl_add_u64 v[186:187], v[222:223], 0, s[4:5]
	s_mov_b32 m0, s42
	s_nop 0
	global_load_lds_dwordx4 v[186:187], off
	v_lshl_add_u64 v[186:187], v[224:225], 0, s[4:5]
	s_mov_b32 m0, s43
	s_nop 0
	global_load_lds_dwordx4 v[186:187], off
	s_waitcnt vmcnt(8)
	s_waitcnt lgkmcnt(0)
	s_barrier
	s_setprio 1
	v_mfma_f32_16x16x32_bf16 v[60:63], v[150:153], v[182:185], v[60:63]
	v_mfma_f32_16x16x32_bf16 v[56:59], v[158:161], v[182:185], v[56:59]
	v_mfma_f32_16x16x32_bf16 v[44:47], v[150:153], v[196:199], v[44:47]
	v_mfma_f32_16x16x32_bf16 v[40:43], v[158:161], v[196:199], v[40:43]
	v_mfma_f32_16x16x32_bf16 v[28:31], v[150:153], v[204:207], v[28:31]
	v_mfma_f32_16x16x32_bf16 v[24:27], v[158:161], v[204:207], v[24:27]
	v_mfma_f32_16x16x32_bf16 v[12:15], v[150:153], v[212:215], v[12:15]
	v_mfma_f32_16x16x32_bf16 v[8:11], v[158:161], v[212:215], v[8:11]
	v_mfma_f32_16x16x32_bf16 v[60:63], v[154:157], v[192:195], v[60:63]
	v_mfma_f32_16x16x32_bf16 v[56:59], v[162:165], v[192:195], v[56:59]
	v_mfma_f32_16x16x32_bf16 v[44:47], v[154:157], v[200:203], v[44:47]
	v_mfma_f32_16x16x32_bf16 v[40:43], v[162:165], v[200:203], v[40:43]
	v_mfma_f32_16x16x32_bf16 v[28:31], v[154:157], v[208:211], v[28:31]
	v_mfma_f32_16x16x32_bf16 v[24:27], v[162:165], v[208:211], v[24:27]
	v_mfma_f32_16x16x32_bf16 v[12:15], v[154:157], v[216:219], v[12:15]
	v_mfma_f32_16x16x32_bf16 v[8:11], v[162:165], v[216:219], v[8:11]
	v_mfma_f32_16x16x32_bf16 v[52:55], v[166:169], v[182:185], v[52:55]
	v_mfma_f32_16x16x32_bf16 v[48:51], v[174:177], v[182:185], v[48:51]
	v_mfma_f32_16x16x32_bf16 v[36:39], v[166:169], v[196:199], v[36:39]
	v_mfma_f32_16x16x32_bf16 v[32:35], v[174:177], v[196:199], v[32:35]
	v_mfma_f32_16x16x32_bf16 v[20:23], v[166:169], v[204:207], v[20:23]
	v_mfma_f32_16x16x32_bf16 v[16:19], v[174:177], v[204:207], v[16:19]
	v_mfma_f32_16x16x32_bf16 v[4:7], v[166:169], v[212:215], v[4:7]
	v_mfma_f32_16x16x32_bf16 v[0:3], v[174:177], v[212:215], v[0:3]
	v_mfma_f32_16x16x32_bf16 v[52:55], v[170:173], v[192:195], v[52:55]
	v_mfma_f32_16x16x32_bf16 v[48:51], v[178:181], v[192:195], v[48:51]
	v_mfma_f32_16x16x32_bf16 v[36:39], v[170:173], v[200:203], v[36:39]
	v_mfma_f32_16x16x32_bf16 v[32:35], v[178:181], v[200:203], v[32:35]
	v_mfma_f32_16x16x32_bf16 v[20:23], v[170:173], v[208:211], v[20:23]
	v_mfma_f32_16x16x32_bf16 v[16:19], v[178:181], v[208:211], v[16:19]
	v_mfma_f32_16x16x32_bf16 v[4:7], v[170:173], v[216:219], v[4:7]
	v_mfma_f32_16x16x32_bf16 v[0:3], v[178:181], v[216:219], v[0:3]
	s_setprio 0
	s_barrier
	s_add_i32 s54, s54, 2
	s_add_u32 s22, s22, 0x100
	s_addc_u32 s23, s23, 0
	s_add_u32 s52, s52, 0x100
	s_addc_u32 s53, s53, 0
	s_branch .LBB0_192

; __device__ __forceinline__ unsigned pk2(float lo, float hi) { return pg8::cvt_pk_bf16(lo, hi); }
; __device__ __forceinline__ float silu_f(float x) { return x * sigmoid_f(x); }
; template <class Epi, class Sched, bool ALIGN_EPI = false, bool SP2 = false>
; __device__ __forceinline__ void gemm_phase(PG8_LAS unsigned char* lds, const Gemm g, const Sched& S, const Epi& E) {
;     ...
;         if constexpr (!Epi::AFTER_DRAIN) { E(acc, cur, wr, wc, fr, fq); S.done(cur); }
;         if (!has_next) break;
;     __device__ __forceinline__ void operator()(const f32x4 (&acc)[2][2][4][2], const pg8::Unit& u, int wr, int wc, int fr, int fq) const {
;         const int row0 = u.pm * 256 + wr * 64 + fr, col = u.pn * 128 + wc * 32 + 8 * fq;
; #pragma unroll
;         for (int ai = 0; ai < 2; ++ai)
; #pragma unroll
;             for (int m = 0; m < 4; ++m) {
;                 const int row = row0 + ai * 128 + m * 16;
;                 const float rs = sumsq ? rsqrtf(sumsq[row] * (1.f / 1024.f) + EPS) : 1.f;
;                 float o[8];
; #pragma unroll
;                 for (int n = 0; n < 2; ++n)
; #pragma unroll
;                     for (int e = 0; e < 4; ++e) { const float g = acc[ai][0][m][n][e] * rs, up = acc[ai][1][m][n][e] * rs; o[4 * n + e] = silu_f(g) * up; }
;                 u32x4 w; w.x = pk2(o[0], o[1]); w.y = pk2(o[2], o[3]); w.z = pk2(o[4], o[5]); w.w = pk2(o[6], o[7]);
;                 *(u32x4*)(H + (size_t)row * DFF + col) = w;
.LBB0_195:
	v_mul_f32_e32 v151, 0xbfb8aa3b, v124
	v_exp_f32_e32 v151, v151
	v_mul_f32_e32 v152, 0xbfb8aa3b, v125
	v_exp_f32_e32 v153, v152
	v_readlane_b32 s22, v235, 33
	v_add_f32_e32 v151, 1.0, v151
	v_rcp_f32_e32 v151, v151
	v_add_f32_e32 v153, 1.0, v153
	v_rcp_f32_e32 v154, v153
	v_lshl_or_b32 v152, s49, 7, v146
	v_mul_f32_e32 v124, v124, v151
	v_mul_f32_e32 v116, v124, v116
	v_mul_f32_e32 v124, v125, v154
	v_mul_f32_e32 v125, 0xbfb8aa3b, v126
	v_exp_f32_e32 v125, v125
	v_mul_f32_e32 v151, 0xbfb8aa3b, v127
	v_exp_f32_e32 v151, v151
	v_mul_f32_e32 v117, v124, v117
	v_add_f32_e32 v124, 1.0, v125
	v_rcp_f32_e32 v124, v124
	v_add_f32_e32 v125, 1.0, v151
	v_mul_f32_e32 v151, 0xbfb8aa3b, v120
	v_rcp_f32_e32 v125, v125
	v_exp_f32_e32 v151, v151
	v_mul_f32_e32 v124, v126, v124
	v_mul_f32_e32 v118, v124, v118
	v_mul_f32_e32 v124, v127, v125
	v_add_f32_e32 v125, 1.0, v151
	v_rcp_f32_e32 v125, v125
	v_mul_f32_e32 v126, 0xbfb8aa3b, v121
	v_exp_f32_e32 v126, v126
	v_mul_f32_e32 v119, v124, v119
	v_mul_f32_e32 v120, v120, v125
	v_mul_f32_e32 v112, v120, v112
	v_add_f32_e32 v120, 1.0, v126
	v_mul_f32_e32 v124, 0xbfb8aa3b, v122
	v_rcp_f32_e32 v120, v120
	v_exp_f32_e32 v124, v124
	v_mul_f32_e32 v125, 0xbfb8aa3b, v123
	v_exp_f32_e32 v125, v125
	v_mul_f32_e32 v120, v121, v120
	v_add_f32_e32 v121, 1.0, v124
	v_rcp_f32_e32 v121, v121
	v_add_f32_e32 v124, 1.0, v125
	v_rcp_f32_e32 v124, v124
	v_mul_f32_e32 v113, v120, v113
	v_mul_f32_e32 v120, v122, v121
	v_mul_f32_e32 v122, 0xbfb8aa3b, v108
	v_mul_f32_e32 v114, v120, v114
	v_mul_f32_e32 v120, v123, v124
	v_readlane_b32 s23, v235, 34
	v_exp_f32_e32 v122, v122
	v_mul_f32_e32 v123, 0xbfb8aa3b, v109
	v_lshl_add_u32 v150, s20, 8, v144
	v_mov_b32_e32 v228, v150
	v_ashrrev_i32_e32 v153, 31, v152
	v_mul_f32_e32 v115, v120, v115
	v_cvt_pk_bf16_f32 v116, v116, v117
	v_cvt_pk_bf16_f32 v117, v118, v119
	v_cvt_pk_bf16_f32 v118, v112, v113
	v_mov_b64_e32 v[112:113], s[22:23]
	v_exp_f32_e32 v123, v123
	v_cvt_pk_bf16_f32 v119, v114, v115
	v_mad_i64_i32 v[120:121], s[22:23], v150, s48, v[112:113]
	v_lshlrev_b64 v[114:115], 1, v[152:153]
	v_lshl_add_u64 v[120:121], v[120:121], 0, v[114:115]
	global_store_dwordx4 v[120:121], v[116:119], off
	s_andn2_b64 vcc, exec, s[0:1]
	s_mov_b64 s[0:1], -1
	v_add_f32_e32 v116, 1.0, v122
	v_rcp_f32_e32 v116, v116
	v_add_f32_e32 v117, 1.0, v123
	v_rcp_f32_e32 v117, v117
	v_or_b32_e32 v118, 16, v150
	v_mul_f32_e32 v108, v108, v116
	v_mul_f32_e32 v100, v108, v100
	v_mul_f32_e32 v108, v109, v117
	v_mul_f32_e32 v109, 0xbfb8aa3b, v110
	v_exp_f32_e32 v109, v109
	v_mul_f32_e32 v116, 0xbfb8aa3b, v111
	v_exp_f32_e32 v116, v116
	v_mul_f32_e32 v101, v108, v101
	v_add_f32_e32 v108, 1.0, v109
	v_rcp_f32_e32 v108, v108
	v_add_f32_e32 v109, 1.0, v116
	v_mul_f32_e32 v116, 0xbfb8aa3b, v104
	v_rcp_f32_e32 v109, v109
	v_exp_f32_e32 v116, v116
	v_mul_f32_e32 v108, v110, v108
	v_mul_f32_e32 v102, v108, v102
	v_mul_f32_e32 v108, v111, v109
	v_add_f32_e32 v109, 1.0, v116
	v_rcp_f32_e32 v109, v109
	v_mul_f32_e32 v110, 0xbfb8aa3b, v105
	v_exp_f32_e32 v110, v110
	v_mul_f32_e32 v103, v108, v103
	v_mul_f32_e32 v104, v104, v109
	v_mul_f32_e32 v104, v104, v96
	v_add_f32_e32 v96, 1.0, v110
	v_mul_f32_e32 v108, 0xbfb8aa3b, v106
	v_rcp_f32_e32 v96, v96
	v_exp_f32_e32 v108, v108
	v_mul_f32_e32 v109, 0xbfb8aa3b, v107
	v_exp_f32_e32 v109, v109
	v_mul_f32_e32 v96, v105, v96
	v_add_f32_e32 v105, 1.0, v108
	v_rcp_f32_e32 v105, v105
	v_add_f32_e32 v108, 1.0, v109
	v_rcp_f32_e32 v108, v108
	v_mul_f32_e32 v109, v96, v97
	v_mul_f32_e32 v96, v106, v105
	v_mul_f32_e32 v105, v96, v98
	v_mul_f32_e32 v96, v107, v108
	v_mul_f32_e32 v99, v96, v99
	v_cvt_pk_bf16_f32 v96, v100, v101
	v_cvt_pk_bf16_f32 v97, v102, v103
	v_mul_f32_e32 v102, 0xbfb8aa3b, v92
	v_exp_f32_e32 v102, v102
	v_mul_f32_e32 v103, 0xbfb8aa3b, v93
	v_exp_f32_e32 v103, v103
	v_mad_i64_i32 v[100:101], s[22:23], v118, s48, v[112:113]
	v_lshl_add_u64 v[100:101], v[100:101], 0, v[114:115]
	v_cvt_pk_bf16_f32 v98, v104, v109
	v_cvt_pk_bf16_f32 v99, v105, v99
	global_store_dwordx4 v[100:101], v[96:99], off
	s_mov_b32 s98, 1
	s_cbranch_vccnz .LBB0_188
	s_andn2_b64 vcc, exec, s[2:3]
	s_cbranch_vccnz .LBB0_187
	s_barrier
	s_branch .LBB0_187
.Lp1_tail:
	s_nop 1
	v_add_f32_e32 v96, 1.0, v102
	v_rcp_f32_e32 v96, v96
	v_add_f32_e32 v97, 1.0, v103
	v_rcp_f32_e32 v97, v97
	v_or_b32_e32 v98, 32, v228
	v_mul_f32_e32 v92, v92, v96
	v_mul_f32_e32 v84, v92, v84
	v_mul_f32_e32 v92, v93, v97
	v_mul_f32_e32 v93, 0xbfb8aa3b, v94
	v_exp_f32_e32 v93, v93
	v_mul_f32_e32 v96, 0xbfb8aa3b, v95
	v_exp_f32_e32 v96, v96
	v_mul_f32_e32 v85, v92, v85
	v_add_f32_e32 v92, 1.0, v93
	v_rcp_f32_e32 v92, v92
	v_add_f32_e32 v93, 1.0, v96
	v_mul_f32_e32 v96, 0xbfb8aa3b, v88
	v_rcp_f32_e32 v93, v93
	v_exp_f32_e32 v96, v96
	v_mul_f32_e32 v92, v94, v92
	v_mul_f32_e32 v86, v92, v86
	v_mul_f32_e32 v92, v95, v93
	v_add_f32_e32 v93, 1.0, v96
	v_rcp_f32_e32 v93, v93
	v_mul_f32_e32 v94, 0xbfb8aa3b, v89
	v_exp_f32_e32 v94, v94
	v_mul_f32_e32 v87, v92, v87
	v_mul_f32_e32 v88, v88, v93
	v_mul_f32_e32 v88, v88, v80
	v_add_f32_e32 v80, 1.0, v94
	v_mul_f32_e32 v92, 0xbfb8aa3b, v90
	v_rcp_f32_e32 v80, v80
	v_exp_f32_e32 v92, v92
	v_mul_f32_e32 v93, 0xbfb8aa3b, v91
	v_exp_f32_e32 v93, v93
	v_mul_f32_e32 v80, v89, v80
	v_add_f32_e32 v89, 1.0, v92
	v_rcp_f32_e32 v89, v89
	v_add_f32_e32 v92, 1.0, v93
	v_rcp_f32_e32 v92, v92
	v_mul_f32_e32 v93, v80, v81
	v_mul_f32_e32 v80, v90, v89
	v_mul_f32_e32 v89, v80, v82
	v_mul_f32_e32 v80, v91, v92
	v_mul_f32_e32 v83, v80, v83
	v_cvt_pk_bf16_f32 v80, v84, v85
	v_cvt_pk_bf16_f32 v81, v86, v87
	v_mul_f32_e32 v86, 0xbfb8aa3b, v76
	v_exp_f32_e32 v86, v86
	v_mul_f32_e32 v87, 0xbfb8aa3b, v77
; __device__ __forceinline__ unsigned pk2(float lo, float hi) { return pg8::cvt_pk_bf16(lo, hi); }
; __device__ __forceinline__ float silu_f(float x) { return x * sigmoid_f(x); }
;     __device__ __forceinline__ void operator()(const f32x4 (&acc)[2][2][4][2], const pg8::Unit& u, int wr, int wc, int fr, int fq) const {
;         const int row0 = u.pm * 256 + wr * 64 + fr, col = u.pn * 128 + wc * 32 + 8 * fq;
; #pragma unroll
;         for (int ai = 0; ai < 2; ++ai)
; #pragma unroll
;             for (int m = 0; m < 4; ++m) {
;                 const int row = row0 + ai * 128 + m * 16;
;                 const float rs = sumsq ? rsqrtf(sumsq[row] * (1.f / 1024.f) + EPS) : 1.f;
;                 float o[8];
; #pragma unroll
;                 for (int n = 0; n < 2; ++n)
; #pragma unroll
;                     for (int e = 0; e < 4; ++e) { const float g = acc[ai][0][m][n][e] * rs, up = acc[ai][1][m][n][e] * rs; o[4 * n + e] = silu_f(g) * up; }
;                 u32x4 w; w.x = pk2(o[0], o[1]); w.y = pk2(o[2], o[3]); w.z = pk2(o[4], o[5]); w.w = pk2(o[6], o[7]);
;                 *(u32x4*)(H + (size_t)row * DFF + col) = w;
	v_exp_f32_e32 v87, v87
	v_mad_i64_i32 v[84:85], s[100:101], v98, s48, v[112:113]
	v_lshl_add_u64 v[84:85], v[84:85], 0, v[114:115]
	v_cvt_pk_bf16_f32 v82, v88, v93
	v_cvt_pk_bf16_f32 v83, v89, v83
	global_store_dwordx4 v[84:85], v[80:83], off
	s_nop 1
	v_add_f32_e32 v80, 1.0, v86
	v_rcp_f32_e32 v80, v80
	v_add_f32_e32 v81, 1.0, v87
	v_rcp_f32_e32 v81, v81
	v_or_b32_e32 v82, 48, v228
	v_mul_f32_e32 v76, v76, v80
	v_mul_f32_e32 v68, v76, v68
	v_mul_f32_e32 v76, v77, v81
	v_mul_f32_e32 v77, 0xbfb8aa3b, v78
	v_exp_f32_e32 v77, v77
	v_mul_f32_e32 v80, 0xbfb8aa3b, v79
	v_exp_f32_e32 v80, v80
	v_mul_f32_e32 v69, v76, v69
	v_add_f32_e32 v76, 1.0, v77
	v_rcp_f32_e32 v76, v76
	v_add_f32_e32 v77, 1.0, v80
	v_mul_f32_e32 v80, 0xbfb8aa3b, v72
	v_rcp_f32_e32 v77, v77
	v_exp_f32_e32 v80, v80
	v_mul_f32_e32 v76, v78, v76
	v_mul_f32_e32 v70, v76, v70
	v_mul_f32_e32 v76, v79, v77
	v_add_f32_e32 v77, 1.0, v80
	v_rcp_f32_e32 v77, v77
	v_mul_f32_e32 v78, 0xbfb8aa3b, v73
	v_exp_f32_e32 v78, v78
	v_mul_f32_e32 v71, v76, v71
	v_mul_f32_e32 v72, v72, v77
	v_mul_f32_e32 v72, v72, v64
	v_add_f32_e32 v64, 1.0, v78
	v_mul_f32_e32 v76, 0xbfb8aa3b, v74
	v_rcp_f32_e32 v64, v64
	v_exp_f32_e32 v76, v76
	v_mul_f32_e32 v77, 0xbfb8aa3b, v75
	v_exp_f32_e32 v77, v77
	v_mul_f32_e32 v64, v73, v64
	v_add_f32_e32 v73, 1.0, v76
	v_rcp_f32_e32 v73, v73
	v_add_f32_e32 v76, 1.0, v77
	v_rcp_f32_e32 v76, v76
	v_mul_f32_e32 v77, v64, v65
	v_mul_f32_e32 v64, v74, v73
	v_mul_f32_e32 v73, v64, v66
	v_mul_f32_e32 v64, v75, v76
	v_mul_f32_e32 v67, v64, v67
	v_cvt_pk_bf16_f32 v64, v68, v69
	v_cvt_pk_bf16_f32 v65, v70, v71
	v_mul_f32_e32 v70, 0xbfb8aa3b, v60
	v_exp_f32_e32 v70, v70
	v_mul_f32_e32 v71, 0xbfb8aa3b, v61
	v_exp_f32_e32 v71, v71
	v_mad_i64_i32 v[68:69], s[100:101], v82, s48, v[112:113]
	v_lshl_add_u64 v[68:69], v[68:69], 0, v[114:115]
	v_cvt_pk_bf16_f32 v66, v72, v77
	v_cvt_pk_bf16_f32 v67, v73, v67
	global_store_dwordx4 v[68:69], v[64:67], off
	s_nop 1
	v_add_f32_e32 v64, 1.0, v70
	v_rcp_f32_e32 v64, v64
	v_add_f32_e32 v65, 1.0, v71
	v_rcp_f32_e32 v65, v65
	v_add_u32_e32 v66, 0x80, v228
	v_mul_f32_e32 v60, v60, v64
	v_mul_f32_e32 v52, v60, v52
	v_mul_f32_e32 v60, v61, v65
	v_mul_f32_e32 v61, 0xbfb8aa3b, v62
	v_exp_f32_e32 v61, v61
	v_mul_f32_e32 v64, 0xbfb8aa3b, v63
	v_exp_f32_e32 v64, v64
	v_mul_f32_e32 v53, v60, v53
	v_add_f32_e32 v60, 1.0, v61
	v_rcp_f32_e32 v60, v60
	v_add_f32_e32 v61, 1.0, v64
	v_mul_f32_e32 v64, 0xbfb8aa3b, v56
	v_rcp_f32_e32 v61, v61
	v_exp_f32_e32 v64, v64
	v_mul_f32_e32 v60, v62, v60
	v_mul_f32_e32 v54, v60, v54
	v_mul_f32_e32 v60, v63, v61
	v_add_f32_e32 v61, 1.0, v64
	v_rcp_f32_e32 v61, v61
	v_mul_f32_e32 v62, 0xbfb8aa3b, v57
	v_exp_f32_e32 v62, v62
	v_mul_f32_e32 v55, v60, v55
	v_mul_f32_e32 v56, v56, v61
	v_mul_f32_e32 v56, v56, v48
	v_add_f32_e32 v48, 1.0, v62
	v_mul_f32_e32 v60, 0xbfb8aa3b, v58
	v_rcp_f32_e32 v48, v48
	v_exp_f32_e32 v60, v60
	v_mul_f32_e32 v61, 0xbfb8aa3b, v59
	v_exp_f32_e32 v61, v61
	v_mul_f32_e32 v48, v57, v48
	v_add_f32_e32 v57, 1.0, v60
	v_rcp_f32_e32 v57, v57
	v_add_f32_e32 v60, 1.0, v61
	v_rcp_f32_e32 v60, v60
	v_mul_f32_e32 v61, v48, v49
	v_mul_f32_e32 v48, v58, v57
	v_mul_f32_e32 v57, v48, v50
	v_mul_f32_e32 v48, v59, v60
	v_mul_f32_e32 v51, v48, v51
	v_cvt_pk_bf16_f32 v48, v52, v53
	v_cvt_pk_bf16_f32 v49, v54, v55
	v_mul_f32_e32 v54, 0xbfb8aa3b, v44
	v_exp_f32_e32 v54, v54
	v_mul_f32_e32 v55, 0xbfb8aa3b, v45
	v_exp_f32_e32 v55, v55
	v_mad_i64_i32 v[52:53], s[100:101], v66, s48, v[112:113]
	v_lshl_add_u64 v[52:53], v[52:53], 0, v[114:115]
	v_cvt_pk_bf16_f32 v50, v56, v61
	v_cvt_pk_bf16_f32 v51, v57, v51
	global_store_dwordx4 v[52:53], v[48:51], off
	s_nop 1
	v_add_f32_e32 v48, 1.0, v54
	v_rcp_f32_e32 v48, v48
	v_add_f32_e32 v49, 1.0, v55
	v_rcp_f32_e32 v49, v49
	v_add_u32_e32 v50, 0x90, v228
	v_mul_f32_e32 v44, v44, v48
	v_mul_f32_e32 v36, v44, v36
	v_mul_f32_e32 v44, v45, v49
	v_mul_f32_e32 v45, 0xbfb8aa3b, v46
	v_exp_f32_e32 v45, v45
	v_mul_f32_e32 v48, 0xbfb8aa3b, v47
	v_exp_f32_e32 v48, v48
	v_mul_f32_e32 v37, v44, v37
	v_add_f32_e32 v44, 1.0, v45
	v_rcp_f32_e32 v44, v44
	v_add_f32_e32 v45, 1.0, v48
	v_mul_f32_e32 v48, 0xbfb8aa3b, v40
	v_rcp_f32_e32 v45, v45
	v_exp_f32_e32 v48, v48
	v_mul_f32_e32 v44, v46, v44
	v_mul_f32_e32 v38, v44, v38
	v_mul_f32_e32 v44, v47, v45
; __device__ __forceinline__ unsigned pk2(float lo, float hi) { return pg8::cvt_pk_bf16(lo, hi); }
; __device__ __forceinline__ float silu_f(float x) { return x * sigmoid_f(x); }
;     __device__ __forceinline__ void operator()(const f32x4 (&acc)[2][2][4][2], const pg8::Unit& u, int wr, int wc, int fr, int fq) const {
;         const int row0 = u.pm * 256 + wr * 64 + fr, col = u.pn * 128 + wc * 32 + 8 * fq;
; #pragma unroll
;         for (int ai = 0; ai < 2; ++ai)
; #pragma unroll
;             for (int m = 0; m < 4; ++m) {
;                 const int row = row0 + ai * 128 + m * 16;
;                 const float rs = sumsq ? rsqrtf(sumsq[row] * (1.f / 1024.f) + EPS) : 1.f;
;                 float o[8];
; #pragma unroll
;                 for (int n = 0; n < 2; ++n)
; #pragma unroll
;                     for (int e = 0; e < 4; ++e) { const float g = acc[ai][0][m][n][e] * rs, up = acc[ai][1][m][n][e] * rs; o[4 * n + e] = silu_f(g) * up; }
;                 u32x4 w; w.x = pk2(o[0], o[1]); w.y = pk2(o[2], o[3]); w.z = pk2(o[4], o[5]); w.w = pk2(o[6], o[7]);
;                 *(u32x4*)(H + (size_t)row * DFF + col) = w;
	v_add_f32_e32 v45, 1.0, v48
	v_rcp_f32_e32 v45, v45
	v_mul_f32_e32 v46, 0xbfb8aa3b, v41
	v_exp_f32_e32 v46, v46
	v_mul_f32_e32 v39, v44, v39
	v_mul_f32_e32 v40, v40, v45
	v_mul_f32_e32 v40, v40, v32
	v_add_f32_e32 v32, 1.0, v46
	v_mul_f32_e32 v44, 0xbfb8aa3b, v42
	v_rcp_f32_e32 v32, v32
	v_exp_f32_e32 v44, v44
	v_mul_f32_e32 v45, 0xbfb8aa3b, v43
	v_exp_f32_e32 v45, v45
	v_mul_f32_e32 v32, v41, v32
	v_add_f32_e32 v41, 1.0, v44
	v_rcp_f32_e32 v41, v41
	v_add_f32_e32 v44, 1.0, v45
	v_rcp_f32_e32 v44, v44
	v_mul_f32_e32 v45, v32, v33
	v_mul_f32_e32 v32, v42, v41
	v_mul_f32_e32 v41, v32, v34
	v_mul_f32_e32 v32, v43, v44
	v_mul_f32_e32 v35, v32, v35
	v_cvt_pk_bf16_f32 v32, v36, v37
	v_cvt_pk_bf16_f32 v33, v38, v39
	v_mul_f32_e32 v38, 0xbfb8aa3b, v28
	v_exp_f32_e32 v38, v38
	v_mul_f32_e32 v39, 0xbfb8aa3b, v29
	v_exp_f32_e32 v39, v39
	v_mad_i64_i32 v[36:37], s[100:101], v50, s48, v[112:113]
	v_lshl_add_u64 v[36:37], v[36:37], 0, v[114:115]
	v_cvt_pk_bf16_f32 v34, v40, v45
	v_cvt_pk_bf16_f32 v35, v41, v35
	global_store_dwordx4 v[36:37], v[32:35], off
	s_nop 1
	v_add_f32_e32 v32, 1.0, v38
	v_rcp_f32_e32 v32, v32
	v_add_f32_e32 v33, 1.0, v39
	v_rcp_f32_e32 v33, v33
	v_add_u32_e32 v34, 0xa0, v228
	v_mul_f32_e32 v28, v28, v32
	v_mul_f32_e32 v20, v28, v20
	v_mul_f32_e32 v28, v29, v33
	v_mul_f32_e32 v29, 0xbfb8aa3b, v30
	v_exp_f32_e32 v29, v29
	v_mul_f32_e32 v32, 0xbfb8aa3b, v31
	v_exp_f32_e32 v32, v32
	v_mul_f32_e32 v21, v28, v21
	v_add_f32_e32 v28, 1.0, v29
	v_rcp_f32_e32 v28, v28
	v_add_f32_e32 v29, 1.0, v32
	v_mul_f32_e32 v32, 0xbfb8aa3b, v24
	v_rcp_f32_e32 v29, v29
	v_exp_f32_e32 v32, v32
	v_mul_f32_e32 v28, v30, v28
	v_mul_f32_e32 v22, v28, v22
	v_mul_f32_e32 v28, v31, v29
	v_add_f32_e32 v29, 1.0, v32
	v_rcp_f32_e32 v29, v29
	v_mul_f32_e32 v30, 0xbfb8aa3b, v25
	v_exp_f32_e32 v30, v30
	v_mul_f32_e32 v23, v28, v23
	v_mul_f32_e32 v24, v24, v29
	v_mul_f32_e32 v24, v24, v16
	v_add_f32_e32 v16, 1.0, v30
	v_mul_f32_e32 v28, 0xbfb8aa3b, v26
	v_rcp_f32_e32 v16, v16
	v_exp_f32_e32 v28, v28
	v_mul_f32_e32 v29, 0xbfb8aa3b, v27
	v_exp_f32_e32 v29, v29
	v_mul_f32_e32 v16, v25, v16
	v_add_f32_e32 v25, 1.0, v28
	v_rcp_f32_e32 v25, v25
	v_add_f32_e32 v28, 1.0, v29
	v_rcp_f32_e32 v28, v28
	v_mul_f32_e32 v29, v16, v17
	v_mul_f32_e32 v16, v26, v25
	v_mul_f32_e32 v25, v16, v18
	v_mul_f32_e32 v16, v27, v28
	v_mul_f32_e32 v19, v16, v19
	v_cvt_pk_bf16_f32 v16, v20, v21
	v_cvt_pk_bf16_f32 v17, v22, v23
	v_mul_f32_e32 v22, 0xbfb8aa3b, v12
	v_exp_f32_e32 v22, v22
	v_mul_f32_e32 v23, 0xbfb8aa3b, v13
	v_exp_f32_e32 v23, v23
	v_mad_i64_i32 v[20:21], s[100:101], v34, s48, v[112:113]
	v_lshl_add_u64 v[20:21], v[20:21], 0, v[114:115]
	v_cvt_pk_bf16_f32 v18, v24, v29
	v_cvt_pk_bf16_f32 v19, v25, v19
	global_store_dwordx4 v[20:21], v[16:19], off
	s_nop 1
	v_add_f32_e32 v16, 1.0, v22
	v_rcp_f32_e32 v16, v16
	v_add_f32_e32 v17, 1.0, v23
	v_rcp_f32_e32 v17, v17
	v_add_u32_e32 v18, 0xb0, v228
	v_mul_f32_e32 v12, v12, v16
	v_mul_f32_e32 v4, v12, v4
	v_mul_f32_e32 v12, v13, v17
	v_mul_f32_e32 v13, 0xbfb8aa3b, v14
	v_exp_f32_e32 v13, v13
	v_mul_f32_e32 v16, 0xbfb8aa3b, v15
	v_exp_f32_e32 v16, v16
	v_mul_f32_e32 v5, v12, v5
	v_add_f32_e32 v12, 1.0, v13
	v_rcp_f32_e32 v12, v12
	v_add_f32_e32 v13, 1.0, v16
	v_mul_f32_e32 v16, 0xbfb8aa3b, v8
	v_rcp_f32_e32 v13, v13
	v_exp_f32_e32 v16, v16
	v_mul_f32_e32 v12, v14, v12
	v_mul_f32_e32 v6, v12, v6
	v_mul_f32_e32 v12, v15, v13
	v_add_f32_e32 v13, 1.0, v16
	v_rcp_f32_e32 v13, v13
	v_mul_f32_e32 v14, 0xbfb8aa3b, v9
	v_exp_f32_e32 v14, v14
	v_mul_f32_e32 v7, v12, v7
	v_mul_f32_e32 v8, v8, v13
	v_mul_f32_e32 v8, v8, v0
	v_add_f32_e32 v0, 1.0, v14
	v_mul_f32_e32 v12, 0xbfb8aa3b, v10
	v_rcp_f32_e32 v0, v0
	v_exp_f32_e32 v12, v12
	v_mul_f32_e32 v13, 0xbfb8aa3b, v11
	v_exp_f32_e32 v13, v13
	v_mul_f32_e32 v0, v9, v0
	v_add_f32_e32 v9, 1.0, v12
	v_rcp_f32_e32 v9, v9
	v_add_f32_e32 v12, 1.0, v13
	v_rcp_f32_e32 v12, v12
	v_mul_f32_e32 v13, v0, v1
	v_mul_f32_e32 v0, v10, v9
	v_mul_f32_e32 v9, v0, v2
	v_mul_f32_e32 v0, v11, v12
	v_mul_f32_e32 v3, v0, v3
	v_cvt_pk_bf16_f32 v0, v4, v5
	v_mad_i64_i32 v[4:5], s[100:101], v18, s48, v[112:113]
	v_lshl_add_u64 v[4:5], v[4:5], 0, v[114:115]
	v_cvt_pk_bf16_f32 v1, v6, v7
	v_cvt_pk_bf16_f32 v2, v8, v13
	v_cvt_pk_bf16_f32 v3, v9, v3
	global_store_dwordx4 v[4:5], v[0:3], off
